# v59 + P3 prologue: W2t DMAs issued before the patch-step store-ack wait and barrier
# speedup vs baseline: 1.0035x; 1.0035x over previous
.LBB0_240:
	v_mov_b32_e32 v8, v196
	s_cmpk_lt_i32 s2, 0x100
	s_cselect_b64 s[42:43], -1, 0
	s_cmpk_gt_i32 s2, 0xff
	v_readfirstlane_b32 s8, v8
	s_cbranch_scc1 .LBB0_246
	s_lshr_b32 s0, s3, 29
	s_add_i32 s6, s2, s0
	s_and_b32 s0, s6, -8
	s_sub_i32 s7, s2, s0
	s_cmp_gt_i32 s7, -1
	s_cbranch_scc0 .LBB0_243
	s_lshl_b32 s9, s7, 5
	s_cbranch_execz .LBB0_244
	s_branch .LBB0_245

.LBB0_246:
	s_add_u32 s60, s52, 0x1700000
	s_addc_u32 s61, s53, 0
	s_add_u32 s36, s52, 0xa000000
	v_cndmask_b32_e64 v0, 0, 1, s[42:43]
	s_addc_u32 s37, s53, 0
	v_cmp_ne_u32_e64 s[6:7], 1, v0
	s_andn2_b64 vcc, exec, s[42:43]
	s_cbranch_vccnz .LBB0_282
	v_ashrrev_i32_e32 v1, 31, v8
	v_lshrrev_b32_e32 v1, 26, v1
	v_add_u32_e32 v1, v8, v1
	v_ashrrev_i32_e32 v9, 6, v1
	v_bfe_i32 v1, v8, 27, 1
	v_lshlrev_b32_e32 v0, 4, v8
	v_lshrrev_b32_e32 v1, 22, v1
	v_add_u32_e32 v1, v0, v1
	v_and_b32_e32 v1, 0xfffffc00, v1
	v_sub_u32_e32 v1, v0, v1
	v_lshrrev_b32_e32 v2, 4, v1
	v_bitop3_b32 v1, v2, v1, 32 bitop3:0x6c
	v_ashrrev_i32_e32 v3, 31, v1
	v_lshrrev_b32_e32 v3, 26, v3
	v_add_u32_e32 v3, v1, v3
	v_lshlrev_b32_e32 v2, 3, v9
	v_ashrrev_i32_e32 v10, 6, v3
	v_and_b32_e32 v3, 0xc0, v3
	v_and_b32_e32 v2, -16, v2
	v_sub_u32_e32 v1, v1, v3
	v_mov_b32_e32 v3, 1
	v_add_u32_e32 v2, v10, v2
	v_ashrrev_i16_sdwa v1, v3, sext(v1) dst_sel:DWORD dst_unused:UNUSED_PAD src0_sel:DWORD src1_sel:BYTE_0
	v_lshlrev_b32_e32 v4, 5, v9
	v_bfe_i32 v11, v1, 0, 16
	v_lshlrev_b32_e32 v1, 1, v2
	v_lshrrev_b32_e32 v5, 2, v2
	v_and_b32_e32 v6, 3, v10
	s_mov_b32 s1, 0x1fffe0
	v_and_b32_e32 v4, 32, v4
	v_and_b32_e32 v1, 24, v1
	v_and_b32_e32 v5, 4, v5
	v_and_or_b32 v6, v2, s1, v6
	v_or3_b32 v1, v6, v5, v1
	v_add_lshl_u32 v4, v4, v11, 1
	v_add_u32_e32 v0, 0x2000, v0
	v_lshl_add_u32 v142, v1, 11, v4
	v_ashrrev_i32_e32 v1, 31, v0
	v_lshrrev_b32_e32 v1, 22, v1
	v_add_u32_e32 v1, v0, v1
	v_ashrrev_i32_e32 v12, 10, v1
	v_mul_i32_i24_e32 v1, 0x400, v12
	v_sub_u32_e32 v0, v0, v1
	v_lshrrev_b32_e32 v1, 4, v0
	v_bitop3_b32 v0, v1, v0, 32 bitop3:0x6c
	v_lshl_add_u32 v140, v2, 11, v4
	v_ashrrev_i32_e32 v2, 31, v0
	v_lshrrev_b32_e32 v2, 26, v2
	v_add_u32_e32 v2, v0, v2
	v_lshlrev_b32_e32 v1, 3, v12
	v_ashrrev_i32_e32 v13, 6, v2
	v_and_b32_e32 v2, 0xc0, v2
	v_and_b32_e32 v1, -16, v1
	v_sub_u32_e32 v0, v0, v2
	v_add_u32_e32 v1, v13, v1
	v_ashrrev_i16_sdwa v0, v3, sext(v0) dst_sel:DWORD dst_unused:UNUSED_PAD src0_sel:DWORD src1_sel:BYTE_0
	v_and_b32_e32 v3, 3, v13
	s_ashr_i32 s9, s8, 6
	v_and_or_b32 v3, v1, s1, v3
	s_ashr_i32 s1, s0, 31
	s_ashr_i32 s63, s62, 31
	s_ashr_i32 s10, s8, 8
	s_lshl_b32 s82, s9, 10
	s_lshl_b64 s[12:13], s[0:1], 19
	s_lshl_b64 s[14:15], s[62:63], 19
	s_add_u32 s16, s22, s14
	v_lshlrev_b32_e32 v4, 5, v12
	v_bfe_i32 v14, v0, 0, 16
	v_lshlrev_b32_e32 v0, 1, v1
	v_lshrrev_b32_e32 v2, 2, v1
	s_addc_u32 s17, s23, s15
	s_add_i32 s83, s82, 0
	v_and_b32_e32 v4, 32, v4
	v_and_b32_e32 v0, 24, v0
	v_and_b32_e32 v2, 4, v2
	s_add_i32 m0, s83, 0x10000
	v_or3_b32 v0, v3, v2, v0
	v_add_lshl_u32 v2, v4, v14, 1
	global_load_lds_dwordx4 v142, s[16:17]
	s_add_i32 m0, s83, 0x12000
	v_lshl_add_u32 v146, v0, 11, v2
	s_add_u32 s14, s16, 0x40000
	global_load_lds_dwordx4 v146, s[16:17]
	s_addc_u32 s15, s17, 0
	s_add_i32 m0, s83, 0x14000
	v_lshl_add_u32 v144, v1, 11, v2
	global_load_lds_dwordx4 v142, s[14:15]
	s_add_i32 m0, s83, 0x16000
	s_add_u32 s12, s28, s12
	s_addc_u32 s13, s29, s13
	s_add_i32 s84, s83, 0x2000
	global_load_lds_dwordx4 v146, s[14:15]
	s_waitcnt vmcnt(0)
	s_barrier
	s_mov_b32 m0, s83
	s_add_u32 s14, s12, 0x40000
	global_load_lds_dwordx4 v140, s[12:13]
	s_mov_b32 m0, s84
	s_addc_u32 s15, s13, 0
	s_add_i32 s85, s83, 0x4000
	global_load_lds_dwordx4 v144, s[12:13]
	s_mov_b32 m0, s85
	s_add_i32 s86, s83, 0x6000
	global_load_lds_dwordx4 v140, s[14:15]
	s_mov_b32 m0, s86
	v_mov_b32_e32 v143, 0
	global_load_lds_dwordx4 v144, s[14:15]
	v_mov_b32_e32 v147, v143
	v_mov_b32_e32 v141, v143
	v_mov_b32_e32 v145, v143
	s_cmp_eq_u32 s10, 1
	s_mov_b32 s63, 0
	v_lshl_add_u64 v[6:7], s[16:17], 0, v[142:143]
	v_lshl_add_u64 v[4:5], s[16:17], 0, v[146:147]
	v_lshl_add_u64 v[0:1], s[12:13], 0, v[140:141]
	s_cselect_b64 s[64:65], -1, 0
	s_cmp_lg_u32 s10, 1
	v_lshl_add_u64 v[2:3], s[12:13], 0, v[144:145]
	s_cbranch_scc1 .LBB0_249
	s_barrier
